# tail hpost: the 24 loads of each 8-token trip issued together up front (counted vmcnt waits + register copies) instead of a load/wait round trip per token
# speedup vs baseline: 1.0081x; 1.0066x over previous
.LBB0_524:
	s_nop 0
	v_lshl_add_u64 v[10:11], s[6:7], 0, v[184:185]
	v_add_co_u32_e64 v24, s[0:1], s14, v10
	v_lshl_add_u64 v[12:13], s[12:13], 0, v[184:185]
	s_nop 0
	v_addc_co_u32_e64 v25, s[0:1], 0, v11, s[0:1]
	v_add_co_u32_e32 v26, vcc, 0x2c000000, v12
	v_add_co_u32_e64 v16, s[0:1], s15, v12
	s_nop 0
	v_addc_co_u32_e32 v27, vcc, 0, v13, vcc
	v_addc_co_u32_e64 v17, s[0:1], 0, v13, s[0:1]
	v_add_co_u32_e64 v18, s[0:1], s16, v12
	v_add_co_u32_e32 v28, vcc, 0x30000000, v12
	s_nop 0
	v_addc_co_u32_e64 v19, s[0:1], 0, v13, s[0:1]
	v_addc_co_u32_e32 v29, vcc, 0, v13, vcc
	v_add_co_u32_e64 v20, s[0:1], s17, v12
	v_add_co_u32_e32 v12, vcc, 0x28000000, v12
	s_nop 0
	v_addc_co_u32_e64 v21, s[0:1], 0, v13, s[0:1]
	v_addc_co_u32_e32 v13, vcc, 0, v13, vcc
	global_load_dwordx4 v[68:71], v[26:27], off
	global_load_dwordx4 v[72:75], v[28:29], off
	global_load_dwordx4 v[76:79], v[12:13], off
	global_load_dwordx4 v[80:83], v[26:27], off offset:1024
	global_load_dwordx4 v[84:87], v[28:29], off offset:1024
	global_load_dwordx4 v[88:91], v[12:13], off offset:1024
	global_load_dwordx4 v[92:95], v[26:27], off offset:2048
	global_load_dwordx4 v[96:99], v[28:29], off offset:2048
	global_load_dwordx4 v[100:103], v[12:13], off offset:2048
	global_load_dwordx4 v[104:107], v[26:27], off offset:3072
	global_load_dwordx4 v[108:111], v[28:29], off offset:3072
	global_load_dwordx4 v[112:115], v[12:13], off offset:3072
	global_load_dwordx4 v[116:119], v[16:17], off
	global_load_dwordx4 v[120:123], v[18:19], off
	global_load_dwordx4 v[124:127], v[20:21], off
	global_load_dwordx4 v[128:131], v[16:17], off offset:1024
	global_load_dwordx4 v[132:135], v[18:19], off offset:1024
	global_load_dwordx4 v[136:139], v[20:21], off offset:1024
	global_load_dwordx4 v[140:143], v[16:17], off offset:2048
	global_load_dwordx4 v[144:147], v[18:19], off offset:2048
	global_load_dwordx4 v[148:151], v[20:21], off offset:2048
	global_load_dwordx4 v[152:155], v[16:17], off offset:3072
	global_load_dwordx4 v[156:159], v[18:19], off offset:3072
	global_load_dwordx4 v[160:163], v[20:21], off offset:3072
	v_add_co_u32_e64 v22, s[0:1], s18, v10
	s_add_u32 s6, s6, 0x4000
	s_nop 0
	v_addc_co_u32_e64 v23, s[0:1], 0, v11, s[0:1]
	v_add_co_u32_e64 v14, s[0:1], s19, v10
	s_addc_u32 s7, s7, 0
	s_nop 0
	v_addc_co_u32_e64 v15, s[0:1], 0, v11, s[0:1]
	s_add_u32 s12, s12, 0x2000
	s_addc_u32 s13, s13, 0
	s_add_i32 s2, s2, -8
	s_cmp_eq_u32 s2, 0
	s_waitcnt vmcnt(21)
	v_mov_b32_e32 v36, v68
	v_mov_b32_e32 v37, v69
	v_mov_b32_e32 v38, v70
	v_mov_b32_e32 v39, v71
	v_mov_b32_e32 v40, v72
	v_mov_b32_e32 v41, v73
	v_mov_b32_e32 v42, v74
	v_mov_b32_e32 v43, v75
	v_mov_b32_e32 v44, v76
	v_mov_b32_e32 v45, v77
	v_mov_b32_e32 v46, v78
	v_mov_b32_e32 v47, v79
	v_lshlrev_b32_e32 v48, 16, v39
	v_and_b32_e32 v49, 0xffff0000, v39
	v_lshlrev_b32_e32 v50, 16, v38
	v_and_b32_e32 v51, 0xffff0000, v38
	v_lshlrev_b32_e32 v38, 16, v37
	v_and_b32_e32 v39, 0xffff0000, v37
	v_lshlrev_b32_e32 v52, 16, v36
	v_and_b32_e32 v53, 0xffff0000, v36
	v_lshlrev_b32_e32 v36, 16, v43
	v_and_b32_e32 v37, 0xffff0000, v43
	v_lshlrev_b32_e32 v54, 16, v42
	v_and_b32_e32 v55, 0xffff0000, v42
	v_lshlrev_b32_e32 v42, 16, v41
	v_and_b32_e32 v43, 0xffff0000, v41
	v_lshlrev_b32_e32 v56, 16, v40
	v_and_b32_e32 v57, 0xffff0000, v40
	v_pk_add_f32 v[36:37], v[48:49], v[36:37]
	v_lshlrev_b32_e32 v40, 16, v47
	v_and_b32_e32 v41, 0xffff0000, v47
	v_pk_add_f32 v[48:49], v[50:51], v[54:55]
	v_lshlrev_b32_e32 v50, 16, v46
	v_and_b32_e32 v51, 0xffff0000, v46
	v_pk_add_f32 v[38:39], v[38:39], v[42:43]
	v_and_b32_e32 v43, 0xffff0000, v45
	v_pk_add_f32 v[46:47], v[52:53], v[56:57]
	v_lshlrev_b32_e32 v42, 16, v45
	v_and_b32_e32 v53, 0xffff0000, v44
	v_mul_f32_e32 v60, 0xbfb8aa3b, v50
	v_mul_f32_e32 v63, 0xbfb8aa3b, v43
	v_pk_mul_f32 v[58:59], v[46:47], v[46:47]
	v_lshlrev_b32_e32 v52, 16, v44
	v_pk_mul_f32 v[56:57], v[38:39], v[38:39]
	v_mul_f32_e32 v62, 0xbfb8aa3b, v42
	v_mul_f32_e32 v65, 0xbfb8aa3b, v53
	v_exp_f32_e32 v60, v60
	v_exp_f32_e32 v63, v63
	v_add_f32_e32 v58, v58, v59
	v_mul_f32_e32 v61, 0xbfb8aa3b, v51
	v_mul_f32_e32 v64, 0xbfb8aa3b, v52
	v_mul_f32_e32 v66, 0xbfb8aa3b, v40
	v_exp_f32_e32 v62, v62
	v_exp_f32_e32 v65, v65
	v_add_f32_e32 v56, v56, v58
	v_pk_mul_f32 v[54:55], v[48:49], v[48:49]
	v_exp_f32_e32 v61, v61
	v_exp_f32_e32 v64, v64
	v_exp_f32_e32 v59, v66
	v_add_f32_e32 v56, v57, v56
	v_add_f32_e32 v54, v54, v56
	v_pk_mul_f32 v[44:45], v[36:37], v[36:37]
	v_add_f32_e32 v56, 1.0, v60
	v_add_f32_e32 v60, 1.0, v63
	v_add_f32_e32 v63, v55, v54
	v_add_f32_e32 v58, 1.0, v62
	v_add_f32_e32 v62, 1.0, v65
	v_add_f32_e32 v44, v44, v63
	v_add_f32_e32 v57, 1.0, v61
	v_add_f32_e32 v61, 1.0, v64
	v_add_f32_e32 v64, 1.0, v59
	v_rcp_f32_e32 v59, v62
	v_add_f32_e32 v62, v45, v44
	ds_bpermute_b32 v63, v31, v62
	v_rcp_f32_e32 v54, v56
	v_rcp_f32_e32 v55, v57
	v_rcp_f32_e32 v56, v58
	v_rcp_f32_e32 v58, v61
	v_mul_f32_e32 v67, 0xbfb8aa3b, v41
	v_pk_mul_f32 v[44:45], v[54:55], v[50:51]
	v_exp_f32_e32 v66, v67
	v_pk_mul_f32 v[50:51], v[58:59], v[52:53]
	s_waitcnt lgkmcnt(0)
	v_add_f32_e32 v52, v62, v63
	ds_bpermute_b32 v53, v32, v52
	v_add_f32_e32 v65, 1.0, v66
	v_rcp_f32_e32 v57, v60
	v_rcp_f32_e32 v60, v64
	v_rcp_f32_e32 v61, v65
	s_waitcnt lgkmcnt(0)
	v_add_f32_e32 v52, v52, v53
	ds_bpermute_b32 v53, v33, v52
	v_pk_mul_f32 v[42:43], v[56:57], v[42:43]
	v_pk_mul_f32 v[40:41], v[60:61], v[40:41]
	s_waitcnt lgkmcnt(0)
	v_add_f32_e32 v52, v52, v53
	ds_bpermute_b32 v53, v34, v52
	s_waitcnt lgkmcnt(0)
	v_add_f32_e32 v52, v52, v53
	v_fmamk_f32 v52, v52, 0x3c000000, v35
	v_mul_f32_e32 v53, 0x4b800000, v52
	v_cmp_gt_f32_e32 vcc, s3, v52
	s_nop 1
	v_cndmask_b32_e32 v52, v52, v53, vcc
	v_rsq_f32_e32 v52, v52
	s_nop 0
	v_mul_f32_e32 v53, 0x45800000, v52
	v_cndmask_b32_e32 v52, v52, v53, vcc
	v_pk_mul_f32 v[46:47], v[46:47], v[52:53] op_sel_hi:[1,0]
	v_pk_mul_f32 v[38:39], v[38:39], v[52:53] op_sel_hi:[1,0]
	v_pk_mul_f32 v[48:49], v[48:49], v[52:53] op_sel_hi:[1,0]
	v_pk_mul_f32 v[36:37], v[36:37], v[52:53] op_sel_hi:[1,0]
	v_pk_mul_f32 v[46:47], v[2:3], v[46:47]
	v_pk_mul_f32 v[38:39], v[4:5], v[38:39]
	v_pk_mul_f32 v[48:49], v[6:7], v[48:49]
	v_pk_mul_f32 v[36:37], v[8:9], v[36:37]
	v_pk_mul_f32 v[46:47], v[50:51], v[46:47]
	v_pk_mul_f32 v[38:39], v[42:43], v[38:39]
	v_pk_mul_f32 v[42:43], v[44:45], v[48:49]
	v_pk_mul_f32 v[40:41], v[40:41], v[36:37]
	v_cvt_pk_bf16_f32 v36, v46, v47
	v_cvt_pk_bf16_f32 v37, v38, v39
	v_cvt_pk_bf16_f32 v38, v42, v43
	v_cvt_pk_bf16_f32 v39, v40, v41
	global_store_dwordx4 v[10:11], v[36:39], off offset:1024
	s_nop 1
	s_waitcnt vmcnt(19)
	v_mov_b32_e32 v36, v80
	v_mov_b32_e32 v37, v81
	v_mov_b32_e32 v38, v82
	v_mov_b32_e32 v39, v83
	v_mov_b32_e32 v40, v84
	v_mov_b32_e32 v41, v85
	v_mov_b32_e32 v42, v86
	v_mov_b32_e32 v43, v87
	v_mov_b32_e32 v44, v88
	v_mov_b32_e32 v45, v89
	v_mov_b32_e32 v46, v90
	v_mov_b32_e32 v47, v91
	s_nop 0
	v_lshlrev_b32_e32 v48, 16, v39
	v_and_b32_e32 v49, 0xffff0000, v39
	v_lshlrev_b32_e32 v50, 16, v43
	v_and_b32_e32 v51, 0xffff0000, v43
	v_lshlrev_b32_e32 v52, 16, v47
	v_and_b32_e32 v53, 0xffff0000, v47
	v_lshlrev_b32_e32 v54, 16, v38
	v_and_b32_e32 v55, 0xffff0000, v38
	v_lshlrev_b32_e32 v38, 16, v42
	v_and_b32_e32 v39, 0xffff0000, v42
	v_lshlrev_b32_e32 v42, 16, v46
	v_and_b32_e32 v43, 0xffff0000, v46
	v_lshlrev_b32_e32 v46, 16, v37
	v_and_b32_e32 v47, 0xffff0000, v37
	v_lshlrev_b32_e32 v56, 16, v41
	v_and_b32_e32 v57, 0xffff0000, v41
	v_lshlrev_b32_e32 v58, 16, v45
	v_and_b32_e32 v59, 0xffff0000, v45
	v_lshlrev_b32_e32 v60, 16, v36
	v_and_b32_e32 v61, 0xffff0000, v36
	v_lshlrev_b32_e32 v36, 16, v40
	v_and_b32_e32 v37, 0xffff0000, v40
	v_pk_add_f32 v[38:39], v[54:55], v[38:39]
	v_mul_f32_e32 v54, 0xbfb8aa3b, v42
	v_mul_f32_e32 v55, 0xbfb8aa3b, v43
	v_pk_add_f32 v[46:47], v[46:47], v[56:57]
	v_mul_f32_e32 v56, 0xbfb8aa3b, v58
	v_mul_f32_e32 v57, 0xbfb8aa3b, v59
	v_pk_add_f32 v[36:37], v[60:61], v[36:37]
	v_exp_f32_e32 v64, v54
	v_exp_f32_e32 v65, v55
	v_exp_f32_e32 v66, v56
	v_exp_f32_e32 v67, v57
	v_pk_mul_f32 v[56:57], v[36:37], v[36:37]
	v_mul_f32_e32 v62, 0xbfb8aa3b, v52
	v_pk_mul_f32 v[54:55], v[46:47], v[46:47]
	v_add_f32_e32 v56, v56, v57
	v_mul_f32_e32 v63, 0xbfb8aa3b, v53
	v_exp_f32_e32 v62, v62
	v_add_f32_e32 v54, v54, v56
	v_lshlrev_b32_e32 v40, 16, v44
	v_and_b32_e32 v41, 0xffff0000, v44
	v_pk_add_f32 v[44:45], v[48:49], v[50:51]
	v_pk_mul_f32 v[50:51], v[38:39], v[38:39]
	v_exp_f32_e32 v63, v63
	v_add_f32_e32 v54, v55, v54
	v_add_f32_e32 v55, 1.0, v64
	v_add_f32_e32 v56, 1.0, v65
	v_add_f32_e32 v57, 1.0, v66
	v_add_f32_e32 v64, 1.0, v67
	v_add_f32_e32 v50, v50, v54
	v_pk_mul_f32 v[48:49], v[44:45], v[44:45]
	v_rcp_f32_e32 v54, v55
	v_rcp_f32_e32 v55, v56
	v_rcp_f32_e32 v56, v57
	v_rcp_f32_e32 v57, v64
	v_add_f32_e32 v64, v51, v50
	v_add_f32_e32 v62, 1.0, v62
	v_add_f32_e32 v48, v48, v64
	v_add_f32_e32 v63, 1.0, v63
	v_rcp_f32_e32 v50, v62
	v_add_f32_e32 v62, v49, v48
	v_rcp_f32_e32 v51, v63
	ds_bpermute_b32 v63, v31, v62
	v_mul_f32_e32 v60, 0xbfb8aa3b, v40
	v_mul_f32_e32 v61, 0xbfb8aa3b, v41
	v_pk_mul_f32 v[50:51], v[50:51], v[52:53]
	v_exp_f32_e32 v60, v60
	s_waitcnt lgkmcnt(0)
	v_add_f32_e32 v52, v62, v63
	ds_bpermute_b32 v53, v32, v52
	v_exp_f32_e32 v61, v61
	v_add_f32_e32 v60, 1.0, v60
	v_rcp_f32_e32 v60, v60
	v_pk_mul_f32 v[42:43], v[54:55], v[42:43]
	s_waitcnt lgkmcnt(0)
	v_add_f32_e32 v52, v52, v53
	ds_bpermute_b32 v53, v33, v52
	v_add_f32_e32 v61, 1.0, v61
	v_rcp_f32_e32 v61, v61
	v_pk_mul_f32 v[48:49], v[56:57], v[58:59]
	s_waitcnt lgkmcnt(0)
	v_add_f32_e32 v52, v52, v53
	ds_bpermute_b32 v53, v34, v52
	v_pk_mul_f32 v[40:41], v[60:61], v[40:41]
	s_waitcnt lgkmcnt(0)
	v_add_f32_e32 v52, v52, v53
	v_fmamk_f32 v52, v52, 0x3c000000, v35
	v_mul_f32_e32 v53, 0x4b800000, v52
	v_cmp_gt_f32_e32 vcc, s3, v52
	s_nop 1
	v_cndmask_b32_e32 v52, v52, v53, vcc
	v_rsq_f32_e32 v52, v52
	s_nop 0
	v_mul_f32_e32 v53, 0x45800000, v52
	v_cndmask_b32_e32 v52, v52, v53, vcc
	v_pk_mul_f32 v[36:37], v[36:37], v[52:53] op_sel_hi:[1,0]
	v_pk_mul_f32 v[46:47], v[46:47], v[52:53] op_sel_hi:[1,0]
	v_pk_mul_f32 v[38:39], v[38:39], v[52:53] op_sel_hi:[1,0]
	v_pk_mul_f32 v[44:45], v[44:45], v[52:53] op_sel_hi:[1,0]
	v_pk_mul_f32 v[36:37], v[2:3], v[36:37]
	v_pk_mul_f32 v[46:47], v[4:5], v[46:47]
	v_pk_mul_f32 v[38:39], v[6:7], v[38:39]
	v_pk_mul_f32 v[44:45], v[8:9], v[44:45]
	v_pk_mul_f32 v[36:37], v[40:41], v[36:37]
	v_pk_mul_f32 v[40:41], v[48:49], v[46:47]
	v_pk_mul_f32 v[38:39], v[42:43], v[38:39]
	v_pk_mul_f32 v[42:43], v[50:51], v[44:45]
	v_cvt_pk_bf16_f32 v36, v36, v37
	v_cvt_pk_bf16_f32 v37, v40, v41
	v_cvt_pk_bf16_f32 v38, v38, v39
	v_cvt_pk_bf16_f32 v39, v42, v43
	global_store_dwordx4 v[10:11], v[36:39], off offset:3072
	s_nop 1
	s_waitcnt vmcnt(17)
	v_mov_b32_e32 v36, v92
	v_mov_b32_e32 v37, v93
	v_mov_b32_e32 v38, v94
	v_mov_b32_e32 v39, v95
	v_mov_b32_e32 v40, v96
	v_mov_b32_e32 v41, v97
	v_mov_b32_e32 v42, v98
	v_mov_b32_e32 v43, v99
	v_mov_b32_e32 v44, v100
	v_mov_b32_e32 v45, v101
	v_mov_b32_e32 v46, v102
	v_mov_b32_e32 v47, v103
	s_nop 0
	v_lshlrev_b32_e32 v10, 16, v39
	v_and_b32_e32 v11, 0xffff0000, v39
	v_lshlrev_b32_e32 v48, 16, v43
	v_and_b32_e32 v49, 0xffff0000, v43
	v_lshlrev_b32_e32 v50, 16, v47
	v_and_b32_e32 v51, 0xffff0000, v47
	v_lshlrev_b32_e32 v52, 16, v38
	v_and_b32_e32 v53, 0xffff0000, v38
	v_lshlrev_b32_e32 v38, 16, v42
	v_and_b32_e32 v39, 0xffff0000, v42
	v_lshlrev_b32_e32 v42, 16, v46
	v_and_b32_e32 v43, 0xffff0000, v46
	v_lshlrev_b32_e32 v46, 16, v37
	v_and_b32_e32 v47, 0xffff0000, v37
	v_lshlrev_b32_e32 v54, 16, v41
	v_and_b32_e32 v55, 0xffff0000, v41
	v_lshlrev_b32_e32 v56, 16, v45
	v_and_b32_e32 v57, 0xffff0000, v45
	v_lshlrev_b32_e32 v58, 16, v36
	v_and_b32_e32 v59, 0xffff0000, v36
	v_lshlrev_b32_e32 v36, 16, v40
	v_and_b32_e32 v37, 0xffff0000, v40
	v_lshlrev_b32_e32 v40, 16, v44
	v_and_b32_e32 v41, 0xffff0000, v44
	v_pk_add_f32 v[38:39], v[52:53], v[38:39]
	v_mul_f32_e32 v52, 0xbfb8aa3b, v42
	v_mul_f32_e32 v53, 0xbfb8aa3b, v43
	v_pk_add_f32 v[44:45], v[46:47], v[54:55]
	v_mul_f32_e32 v54, 0xbfb8aa3b, v56
	v_mul_f32_e32 v55, 0xbfb8aa3b, v57
	v_pk_add_f32 v[36:37], v[58:59], v[36:37]
	v_exp_f32_e32 v62, v52
	v_exp_f32_e32 v63, v53
	v_exp_f32_e32 v64, v54
	v_exp_f32_e32 v65, v55
	v_pk_mul_f32 v[54:55], v[36:37], v[36:37]
	v_mul_f32_e32 v60, 0xbfb8aa3b, v50
	v_pk_mul_f32 v[52:53], v[44:45], v[44:45]
	v_add_f32_e32 v54, v54, v55
	v_mul_f32_e32 v61, 0xbfb8aa3b, v51
	v_exp_f32_e32 v60, v60
	v_add_f32_e32 v52, v52, v54
	v_pk_add_f32 v[10:11], v[10:11], v[48:49]
	v_pk_mul_f32 v[48:49], v[38:39], v[38:39]
	v_exp_f32_e32 v61, v61
	v_add_f32_e32 v52, v53, v52
	v_add_f32_e32 v53, 1.0, v62
	v_add_f32_e32 v54, 1.0, v63
	v_add_f32_e32 v55, 1.0, v64
	v_add_f32_e32 v62, 1.0, v65
	v_add_f32_e32 v48, v48, v52
	v_pk_mul_f32 v[46:47], v[10:11], v[10:11]
	v_rcp_f32_e32 v52, v53
	v_rcp_f32_e32 v53, v54
	v_rcp_f32_e32 v54, v55
	v_rcp_f32_e32 v55, v62
	v_add_f32_e32 v62, v49, v48
	v_add_f32_e32 v60, 1.0, v60
	v_add_f32_e32 v46, v46, v62
	v_add_f32_e32 v61, 1.0, v61
	v_rcp_f32_e32 v48, v60
	v_add_f32_e32 v60, v47, v46
	v_rcp_f32_e32 v49, v61
	ds_bpermute_b32 v61, v31, v60
	v_mul_f32_e32 v58, 0xbfb8aa3b, v40
	v_mul_f32_e32 v59, 0xbfb8aa3b, v41
	v_pk_mul_f32 v[48:49], v[48:49], v[50:51]
	v_exp_f32_e32 v58, v58
	s_waitcnt lgkmcnt(0)
	v_add_f32_e32 v50, v60, v61
	ds_bpermute_b32 v51, v32, v50
	v_exp_f32_e32 v59, v59
	v_add_f32_e32 v58, 1.0, v58
	v_rcp_f32_e32 v58, v58
	v_pk_mul_f32 v[42:43], v[52:53], v[42:43]
	s_waitcnt lgkmcnt(0)
	v_add_f32_e32 v50, v50, v51
	ds_bpermute_b32 v51, v33, v50
	v_add_f32_e32 v59, 1.0, v59
	v_rcp_f32_e32 v59, v59
	v_pk_mul_f32 v[46:47], v[54:55], v[56:57]
	s_waitcnt lgkmcnt(0)
	v_add_f32_e32 v50, v50, v51
	ds_bpermute_b32 v51, v34, v50
	v_pk_mul_f32 v[40:41], v[58:59], v[40:41]
	s_waitcnt lgkmcnt(0)
	v_add_f32_e32 v50, v50, v51
	v_fmamk_f32 v50, v50, 0x3c000000, v35
	v_mul_f32_e32 v51, 0x4b800000, v50
	v_cmp_gt_f32_e32 vcc, s3, v50
	s_nop 1
	v_cndmask_b32_e32 v50, v50, v51, vcc
	v_rsq_f32_e32 v50, v50
	s_nop 0
	v_mul_f32_e32 v51, 0x45800000, v50
	v_cndmask_b32_e32 v50, v50, v51, vcc
	v_pk_mul_f32 v[36:37], v[36:37], v[50:51] op_sel_hi:[1,0]
	v_pk_mul_f32 v[44:45], v[44:45], v[50:51] op_sel_hi:[1,0]
	v_pk_mul_f32 v[38:39], v[38:39], v[50:51] op_sel_hi:[1,0]
	v_pk_mul_f32 v[10:11], v[10:11], v[50:51] op_sel_hi:[1,0]
	v_pk_mul_f32 v[36:37], v[2:3], v[36:37]
	v_pk_mul_f32 v[44:45], v[4:5], v[44:45]
	v_pk_mul_f32 v[38:39], v[6:7], v[38:39]
	v_pk_mul_f32 v[10:11], v[8:9], v[10:11]
	v_pk_mul_f32 v[36:37], v[40:41], v[36:37]
	v_pk_mul_f32 v[40:41], v[46:47], v[44:45]
	v_pk_mul_f32 v[38:39], v[42:43], v[38:39]
	v_pk_mul_f32 v[10:11], v[48:49], v[10:11]
	v_cvt_pk_bf16_f32 v36, v36, v37
	v_cvt_pk_bf16_f32 v37, v40, v41
	v_cvt_pk_bf16_f32 v38, v38, v39
	v_cvt_pk_bf16_f32 v39, v10, v11
	global_store_dwordx4 v[24:25], v[36:39], off offset:1024
	s_nop 1
	s_waitcnt vmcnt(15)
	v_mov_b32_e32 v36, v104
	v_mov_b32_e32 v37, v105
	v_mov_b32_e32 v38, v106
	v_mov_b32_e32 v39, v107
	v_mov_b32_e32 v40, v108
	v_mov_b32_e32 v41, v109
	v_mov_b32_e32 v42, v110
	v_mov_b32_e32 v43, v111
	v_mov_b32_e32 v44, v112
	v_mov_b32_e32 v45, v113
	v_mov_b32_e32 v46, v114
	v_mov_b32_e32 v47, v115
	s_nop 0
	v_lshlrev_b32_e32 v10, 16, v39
	v_and_b32_e32 v11, 0xffff0000, v39
	v_lshlrev_b32_e32 v12, 16, v43
	v_and_b32_e32 v13, 0xffff0000, v43
	v_lshlrev_b32_e32 v26, 16, v47
	v_and_b32_e32 v27, 0xffff0000, v47
	v_lshlrev_b32_e32 v28, 16, v38
	v_and_b32_e32 v29, 0xffff0000, v38
	v_lshlrev_b32_e32 v38, 16, v42
	v_and_b32_e32 v39, 0xffff0000, v42
	v_lshlrev_b32_e32 v42, 16, v46
	v_and_b32_e32 v43, 0xffff0000, v46
	v_lshlrev_b32_e32 v46, 16, v37
	v_and_b32_e32 v47, 0xffff0000, v37
	v_lshlrev_b32_e32 v48, 16, v41
	v_and_b32_e32 v49, 0xffff0000, v41
	v_lshlrev_b32_e32 v50, 16, v45
	v_and_b32_e32 v51, 0xffff0000, v45
	v_lshlrev_b32_e32 v52, 16, v36
	v_and_b32_e32 v53, 0xffff0000, v36
	v_lshlrev_b32_e32 v36, 16, v40
	v_and_b32_e32 v37, 0xffff0000, v40
	v_pk_add_f32 v[10:11], v[10:11], v[12:13]
	v_pk_add_f32 v[12:13], v[28:29], v[38:39]
	v_mul_f32_e32 v54, 0xbfb8aa3b, v42
	v_mul_f32_e32 v55, 0xbfb8aa3b, v43
	v_pk_add_f32 v[28:29], v[46:47], v[48:49]
	v_mul_f32_e32 v48, 0xbfb8aa3b, v50
	v_mul_f32_e32 v49, 0xbfb8aa3b, v51
	v_pk_add_f32 v[36:37], v[52:53], v[36:37]
	v_exp_f32_e32 v54, v54
	v_exp_f32_e32 v55, v55
	v_exp_f32_e32 v58, v48
	v_exp_f32_e32 v59, v49
	v_pk_mul_f32 v[48:49], v[36:37], v[36:37]
	v_pk_mul_f32 v[46:47], v[28:29], v[28:29]
	v_add_f32_e32 v48, v48, v49
	v_mul_f32_e32 v56, 0xbfb8aa3b, v26
	v_add_f32_e32 v46, v46, v48
	v_lshlrev_b32_e32 v40, 16, v44
	v_and_b32_e32 v41, 0xffff0000, v44
	v_mul_f32_e32 v57, 0xbfb8aa3b, v27
	v_pk_mul_f32 v[44:45], v[12:13], v[12:13]
	v_exp_f32_e32 v56, v56
	v_add_f32_e32 v46, v47, v46
	v_exp_f32_e32 v57, v57
	v_add_f32_e32 v47, 1.0, v54
	v_add_f32_e32 v48, 1.0, v55
	v_add_f32_e32 v49, 1.0, v58
	v_add_f32_e32 v54, 1.0, v59
	v_add_f32_e32 v44, v44, v46
	v_pk_mul_f32 v[38:39], v[10:11], v[10:11]
	v_rcp_f32_e32 v46, v47
	v_rcp_f32_e32 v47, v48
	v_rcp_f32_e32 v48, v49
	v_rcp_f32_e32 v49, v54
	v_add_f32_e32 v54, v45, v44
	v_add_f32_e32 v38, v38, v54
	v_add_f32_e32 v55, 1.0, v56
	v_add_f32_e32 v54, v39, v38
	v_add_f32_e32 v56, 1.0, v57
	v_rcp_f32_e32 v44, v55
	ds_bpermute_b32 v55, v31, v54
	v_rcp_f32_e32 v45, v56
	v_mul_f32_e32 v52, 0xbfb8aa3b, v40
	v_mul_f32_e32 v53, 0xbfb8aa3b, v41
	v_exp_f32_e32 v52, v52
	v_pk_mul_f32 v[26:27], v[44:45], v[26:27]
	s_waitcnt lgkmcnt(0)
	v_add_f32_e32 v44, v54, v55
	ds_bpermute_b32 v45, v32, v44
	v_exp_f32_e32 v53, v53
	v_add_f32_e32 v52, 1.0, v52
	v_rcp_f32_e32 v52, v52
	v_pk_mul_f32 v[38:39], v[46:47], v[42:43]
	s_waitcnt lgkmcnt(0)
	v_add_f32_e32 v44, v44, v45
	ds_bpermute_b32 v45, v33, v44
	v_add_f32_e32 v53, 1.0, v53
	v_rcp_f32_e32 v53, v53
	v_pk_mul_f32 v[42:43], v[48:49], v[50:51]
	s_waitcnt lgkmcnt(0)
	v_add_f32_e32 v44, v44, v45
	ds_bpermute_b32 v45, v34, v44
	v_pk_mul_f32 v[40:41], v[52:53], v[40:41]
	s_waitcnt lgkmcnt(0)
	v_add_f32_e32 v44, v44, v45
	v_fmamk_f32 v44, v44, 0x3c000000, v35
	v_mul_f32_e32 v45, 0x4b800000, v44
	v_cmp_gt_f32_e32 vcc, s3, v44
	s_nop 1
	v_cndmask_b32_e32 v44, v44, v45, vcc
	v_rsq_f32_e32 v44, v44
	s_nop 0
	v_mul_f32_e32 v45, 0x45800000, v44
	v_cndmask_b32_e32 v44, v44, v45, vcc
	v_pk_mul_f32 v[36:37], v[36:37], v[44:45] op_sel_hi:[1,0]
	v_pk_mul_f32 v[28:29], v[28:29], v[44:45] op_sel_hi:[1,0]
	v_pk_mul_f32 v[12:13], v[12:13], v[44:45] op_sel_hi:[1,0]
	v_pk_mul_f32 v[10:11], v[10:11], v[44:45] op_sel_hi:[1,0]
	v_pk_mul_f32 v[36:37], v[2:3], v[36:37]
	v_pk_mul_f32 v[28:29], v[4:5], v[28:29]
	v_pk_mul_f32 v[12:13], v[6:7], v[12:13]
	v_pk_mul_f32 v[10:11], v[8:9], v[10:11]
	v_pk_mul_f32 v[36:37], v[40:41], v[36:37]
	v_pk_mul_f32 v[28:29], v[42:43], v[28:29]
	v_pk_mul_f32 v[12:13], v[38:39], v[12:13]
	v_pk_mul_f32 v[26:27], v[26:27], v[10:11]
	v_cvt_pk_bf16_f32 v10, v36, v37
	v_cvt_pk_bf16_f32 v11, v28, v29
	v_cvt_pk_bf16_f32 v12, v12, v13
	v_cvt_pk_bf16_f32 v13, v26, v27
	global_store_dwordx4 v[24:25], v[10:13], off offset:3072
	s_nop 1
	s_waitcnt vmcnt(13)
	v_mov_b32_e32 v10, v116
	v_mov_b32_e32 v11, v117
	v_mov_b32_e32 v12, v118
	v_mov_b32_e32 v13, v119
	v_mov_b32_e32 v24, v120
	v_mov_b32_e32 v25, v121
	v_mov_b32_e32 v26, v122
	v_mov_b32_e32 v27, v123
	v_mov_b32_e32 v36, v124
	v_mov_b32_e32 v37, v125
	v_mov_b32_e32 v38, v126
	v_mov_b32_e32 v39, v127
	s_nop 0
	v_lshlrev_b32_e32 v28, 16, v13
	v_and_b32_e32 v29, 0xffff0000, v13
	v_lshlrev_b32_e32 v40, 16, v27
	v_and_b32_e32 v41, 0xffff0000, v27
	v_lshlrev_b32_e32 v42, 16, v39
	v_and_b32_e32 v43, 0xffff0000, v39
	v_lshlrev_b32_e32 v44, 16, v12
	v_and_b32_e32 v45, 0xffff0000, v12
	v_lshlrev_b32_e32 v12, 16, v26
	v_and_b32_e32 v13, 0xffff0000, v26
	v_lshlrev_b32_e32 v26, 16, v38
	v_and_b32_e32 v27, 0xffff0000, v38
	v_lshlrev_b32_e32 v38, 16, v11
	v_and_b32_e32 v39, 0xffff0000, v11
	v_lshlrev_b32_e32 v46, 16, v25
	v_and_b32_e32 v47, 0xffff0000, v25
	v_lshlrev_b32_e32 v48, 16, v37
	v_and_b32_e32 v49, 0xffff0000, v37
	v_lshlrev_b32_e32 v50, 16, v10
	v_and_b32_e32 v51, 0xffff0000, v10
	v_lshlrev_b32_e32 v10, 16, v24
	v_and_b32_e32 v11, 0xffff0000, v24
	v_lshlrev_b32_e32 v24, 16, v36
	v_and_b32_e32 v25, 0xffff0000, v36
	v_pk_add_f32 v[12:13], v[44:45], v[12:13]
	v_mul_f32_e32 v44, 0xbfb8aa3b, v26
	v_mul_f32_e32 v45, 0xbfb8aa3b, v27
	v_pk_add_f32 v[36:37], v[38:39], v[46:47]
	v_mul_f32_e32 v46, 0xbfb8aa3b, v48
	v_mul_f32_e32 v47, 0xbfb8aa3b, v49
	v_pk_add_f32 v[10:11], v[50:51], v[10:11]
	v_exp_f32_e32 v54, v44
	v_exp_f32_e32 v55, v45
	v_exp_f32_e32 v56, v46
	v_exp_f32_e32 v57, v47
	v_pk_mul_f32 v[46:47], v[10:11], v[10:11]
	v_mul_f32_e32 v52, 0xbfb8aa3b, v42
	v_pk_mul_f32 v[44:45], v[36:37], v[36:37]
	v_add_f32_e32 v46, v46, v47
	v_mul_f32_e32 v53, 0xbfb8aa3b, v43
	v_exp_f32_e32 v52, v52
	v_add_f32_e32 v44, v44, v46
	v_pk_add_f32 v[28:29], v[28:29], v[40:41]
	v_pk_mul_f32 v[40:41], v[12:13], v[12:13]
	v_exp_f32_e32 v53, v53
	v_add_f32_e32 v44, v45, v44
	v_add_f32_e32 v45, 1.0, v54
	v_add_f32_e32 v46, 1.0, v55
	v_add_f32_e32 v47, 1.0, v56
	v_add_f32_e32 v54, 1.0, v57
	v_add_f32_e32 v40, v40, v44
	v_pk_mul_f32 v[38:39], v[28:29], v[28:29]
	v_rcp_f32_e32 v44, v45
	v_rcp_f32_e32 v45, v46
	v_rcp_f32_e32 v46, v47
	v_rcp_f32_e32 v47, v54
	v_add_f32_e32 v54, v41, v40
	v_add_f32_e32 v52, 1.0, v52
	v_add_f32_e32 v38, v38, v54
	v_add_f32_e32 v53, 1.0, v53
	v_rcp_f32_e32 v40, v52
	v_add_f32_e32 v52, v39, v38
	v_rcp_f32_e32 v41, v53
	ds_bpermute_b32 v53, v31, v52
	v_mul_f32_e32 v50, 0xbfb8aa3b, v24
	v_mul_f32_e32 v51, 0xbfb8aa3b, v25
	v_pk_mul_f32 v[40:41], v[40:41], v[42:43]
	v_exp_f32_e32 v50, v50
	s_waitcnt lgkmcnt(0)
	v_add_f32_e32 v42, v52, v53
	ds_bpermute_b32 v43, v32, v42
	v_exp_f32_e32 v51, v51
	v_add_f32_e32 v50, 1.0, v50
	v_rcp_f32_e32 v50, v50
	v_pk_mul_f32 v[26:27], v[44:45], v[26:27]
	s_waitcnt lgkmcnt(0)
	v_add_f32_e32 v42, v42, v43
	ds_bpermute_b32 v43, v33, v42
	v_add_f32_e32 v51, 1.0, v51
	v_rcp_f32_e32 v51, v51
	v_pk_mul_f32 v[38:39], v[46:47], v[48:49]
	s_waitcnt lgkmcnt(0)
	v_add_f32_e32 v42, v42, v43
	ds_bpermute_b32 v43, v34, v42
	v_pk_mul_f32 v[24:25], v[50:51], v[24:25]
	s_waitcnt lgkmcnt(0)
	v_add_f32_e32 v42, v42, v43
	v_fmamk_f32 v42, v42, 0x3c000000, v35
	v_mul_f32_e32 v43, 0x4b800000, v42
	v_cmp_gt_f32_e32 vcc, s3, v42
	s_nop 1
	v_cndmask_b32_e32 v42, v42, v43, vcc
	v_rsq_f32_e32 v42, v42
	s_nop 0
	v_mul_f32_e32 v43, 0x45800000, v42
	v_cndmask_b32_e32 v42, v42, v43, vcc
	v_pk_mul_f32 v[10:11], v[10:11], v[42:43] op_sel_hi:[1,0]
	v_pk_mul_f32 v[36:37], v[36:37], v[42:43] op_sel_hi:[1,0]
	v_pk_mul_f32 v[12:13], v[12:13], v[42:43] op_sel_hi:[1,0]
	v_pk_mul_f32 v[28:29], v[28:29], v[42:43] op_sel_hi:[1,0]
	v_pk_mul_f32 v[10:11], v[2:3], v[10:11]
	v_pk_mul_f32 v[36:37], v[4:5], v[36:37]
	v_pk_mul_f32 v[12:13], v[6:7], v[12:13]
	v_pk_mul_f32 v[28:29], v[8:9], v[28:29]
	v_pk_mul_f32 v[10:11], v[24:25], v[10:11]
	v_pk_mul_f32 v[24:25], v[38:39], v[36:37]
	v_pk_mul_f32 v[12:13], v[26:27], v[12:13]
	v_pk_mul_f32 v[26:27], v[40:41], v[28:29]
	v_cvt_pk_bf16_f32 v10, v10, v11
	v_cvt_pk_bf16_f32 v11, v24, v25
	v_cvt_pk_bf16_f32 v12, v12, v13
	v_cvt_pk_bf16_f32 v13, v26, v27
	global_store_dwordx4 v[22:23], v[10:13], off offset:1024
	s_nop 1
	s_waitcnt vmcnt(11)
	v_mov_b32_e32 v10, v128
	v_mov_b32_e32 v11, v129
	v_mov_b32_e32 v12, v130
	v_mov_b32_e32 v13, v131
	v_mov_b32_e32 v24, v132
	v_mov_b32_e32 v25, v133
	v_mov_b32_e32 v26, v134
	v_mov_b32_e32 v27, v135
	v_mov_b32_e32 v36, v136
	v_mov_b32_e32 v37, v137
	v_mov_b32_e32 v38, v138
	v_mov_b32_e32 v39, v139
	s_nop 0
	v_lshlrev_b32_e32 v28, 16, v13
	v_and_b32_e32 v29, 0xffff0000, v13
	v_lshlrev_b32_e32 v40, 16, v27
	v_and_b32_e32 v41, 0xffff0000, v27
	v_lshlrev_b32_e32 v42, 16, v39
	v_and_b32_e32 v43, 0xffff0000, v39
	v_lshlrev_b32_e32 v44, 16, v12
	v_and_b32_e32 v45, 0xffff0000, v12
	v_lshlrev_b32_e32 v12, 16, v26
	v_and_b32_e32 v13, 0xffff0000, v26
	v_lshlrev_b32_e32 v26, 16, v38
	v_and_b32_e32 v27, 0xffff0000, v38
	v_lshlrev_b32_e32 v38, 16, v11
	v_and_b32_e32 v39, 0xffff0000, v11
	v_lshlrev_b32_e32 v46, 16, v25
	v_and_b32_e32 v47, 0xffff0000, v25
	v_lshlrev_b32_e32 v48, 16, v37
	v_and_b32_e32 v49, 0xffff0000, v37
	v_lshlrev_b32_e32 v50, 16, v10
	v_and_b32_e32 v51, 0xffff0000, v10
	v_lshlrev_b32_e32 v10, 16, v24
	v_and_b32_e32 v11, 0xffff0000, v24
	v_lshlrev_b32_e32 v24, 16, v36
	v_and_b32_e32 v25, 0xffff0000, v36
	v_pk_add_f32 v[12:13], v[44:45], v[12:13]
	v_mul_f32_e32 v44, 0xbfb8aa3b, v26
	v_mul_f32_e32 v45, 0xbfb8aa3b, v27
	v_pk_add_f32 v[36:37], v[38:39], v[46:47]
	v_mul_f32_e32 v46, 0xbfb8aa3b, v48
	v_mul_f32_e32 v47, 0xbfb8aa3b, v49
	v_pk_add_f32 v[10:11], v[50:51], v[10:11]
	v_exp_f32_e32 v54, v44
	v_exp_f32_e32 v55, v45
	v_exp_f32_e32 v56, v46
	v_exp_f32_e32 v57, v47
	v_pk_mul_f32 v[46:47], v[10:11], v[10:11]
	v_mul_f32_e32 v52, 0xbfb8aa3b, v42
	v_pk_mul_f32 v[44:45], v[36:37], v[36:37]
	v_add_f32_e32 v46, v46, v47
	v_mul_f32_e32 v53, 0xbfb8aa3b, v43
	v_exp_f32_e32 v52, v52
	v_add_f32_e32 v44, v44, v46
	v_pk_add_f32 v[28:29], v[28:29], v[40:41]
	v_pk_mul_f32 v[40:41], v[12:13], v[12:13]
	v_exp_f32_e32 v53, v53
	v_add_f32_e32 v44, v45, v44
	v_add_f32_e32 v45, 1.0, v54
	v_add_f32_e32 v46, 1.0, v55
	v_add_f32_e32 v47, 1.0, v56
	v_add_f32_e32 v54, 1.0, v57
	v_add_f32_e32 v40, v40, v44
	v_pk_mul_f32 v[38:39], v[28:29], v[28:29]
	v_rcp_f32_e32 v44, v45
	v_rcp_f32_e32 v45, v46
	v_rcp_f32_e32 v46, v47
	v_rcp_f32_e32 v47, v54
	v_add_f32_e32 v54, v41, v40
	v_add_f32_e32 v52, 1.0, v52
	v_add_f32_e32 v38, v38, v54
	v_add_f32_e32 v53, 1.0, v53
	v_rcp_f32_e32 v40, v52
	v_add_f32_e32 v52, v39, v38
	v_rcp_f32_e32 v41, v53
	ds_bpermute_b32 v53, v31, v52
	v_mul_f32_e32 v50, 0xbfb8aa3b, v24
	v_mul_f32_e32 v51, 0xbfb8aa3b, v25
	v_pk_mul_f32 v[40:41], v[40:41], v[42:43]
	v_exp_f32_e32 v50, v50
	s_waitcnt lgkmcnt(0)
	v_add_f32_e32 v42, v52, v53
	ds_bpermute_b32 v43, v32, v42
	v_exp_f32_e32 v51, v51
	v_add_f32_e32 v50, 1.0, v50
	v_rcp_f32_e32 v50, v50
	v_pk_mul_f32 v[26:27], v[44:45], v[26:27]
	s_waitcnt lgkmcnt(0)
	v_add_f32_e32 v42, v42, v43
	ds_bpermute_b32 v43, v33, v42
	v_add_f32_e32 v51, 1.0, v51
	v_rcp_f32_e32 v51, v51
	v_pk_mul_f32 v[38:39], v[46:47], v[48:49]
	s_waitcnt lgkmcnt(0)
	v_add_f32_e32 v42, v42, v43
	ds_bpermute_b32 v43, v34, v42
	v_pk_mul_f32 v[24:25], v[50:51], v[24:25]
	s_waitcnt lgkmcnt(0)
	v_add_f32_e32 v42, v42, v43
	v_fmamk_f32 v42, v42, 0x3c000000, v35
	v_mul_f32_e32 v43, 0x4b800000, v42
	v_cmp_gt_f32_e32 vcc, s3, v42
	s_nop 1
	v_cndmask_b32_e32 v42, v42, v43, vcc
	v_rsq_f32_e32 v42, v42
	s_nop 0
	v_mul_f32_e32 v43, 0x45800000, v42
	v_cndmask_b32_e32 v42, v42, v43, vcc
	v_pk_mul_f32 v[10:11], v[10:11], v[42:43] op_sel_hi:[1,0]
	v_pk_mul_f32 v[36:37], v[36:37], v[42:43] op_sel_hi:[1,0]
	v_pk_mul_f32 v[12:13], v[12:13], v[42:43] op_sel_hi:[1,0]
	v_pk_mul_f32 v[28:29], v[28:29], v[42:43] op_sel_hi:[1,0]
	v_pk_mul_f32 v[10:11], v[2:3], v[10:11]
	v_pk_mul_f32 v[36:37], v[4:5], v[36:37]
	v_pk_mul_f32 v[12:13], v[6:7], v[12:13]
	v_pk_mul_f32 v[28:29], v[8:9], v[28:29]
	v_pk_mul_f32 v[10:11], v[24:25], v[10:11]
	v_pk_mul_f32 v[24:25], v[38:39], v[36:37]
	v_pk_mul_f32 v[12:13], v[26:27], v[12:13]
	v_pk_mul_f32 v[26:27], v[40:41], v[28:29]
	v_cvt_pk_bf16_f32 v10, v10, v11
	v_cvt_pk_bf16_f32 v11, v24, v25
	v_cvt_pk_bf16_f32 v12, v12, v13
	v_cvt_pk_bf16_f32 v13, v26, v27
	global_store_dwordx4 v[22:23], v[10:13], off offset:3072
	s_nop 1
	s_waitcnt vmcnt(9)
	v_mov_b32_e32 v10, v140
	v_mov_b32_e32 v11, v141
	v_mov_b32_e32 v12, v142
	v_mov_b32_e32 v13, v143
	v_mov_b32_e32 v22, v144
	v_mov_b32_e32 v23, v145
	v_mov_b32_e32 v24, v146
	v_mov_b32_e32 v25, v147
	v_mov_b32_e32 v26, v148
	v_mov_b32_e32 v27, v149
	v_mov_b32_e32 v28, v150
	v_mov_b32_e32 v29, v151
	s_nop 0
	v_lshlrev_b32_e32 v36, 16, v13
	v_and_b32_e32 v37, 0xffff0000, v13
	v_lshlrev_b32_e32 v38, 16, v25
	v_and_b32_e32 v39, 0xffff0000, v25
	v_lshlrev_b32_e32 v40, 16, v29
	v_and_b32_e32 v41, 0xffff0000, v29
	v_lshlrev_b32_e32 v42, 16, v12
	v_and_b32_e32 v43, 0xffff0000, v12
	v_lshlrev_b32_e32 v12, 16, v24
	v_and_b32_e32 v13, 0xffff0000, v24
	v_lshlrev_b32_e32 v24, 16, v28
	v_and_b32_e32 v25, 0xffff0000, v28
	v_lshlrev_b32_e32 v28, 16, v11
	v_and_b32_e32 v29, 0xffff0000, v11
	v_lshlrev_b32_e32 v44, 16, v23
	v_and_b32_e32 v45, 0xffff0000, v23
	v_lshlrev_b32_e32 v46, 16, v27
	v_and_b32_e32 v47, 0xffff0000, v27
	v_lshlrev_b32_e32 v48, 16, v10
	v_and_b32_e32 v49, 0xffff0000, v10
	v_lshlrev_b32_e32 v10, 16, v22
	v_and_b32_e32 v11, 0xffff0000, v22
	v_pk_add_f32 v[12:13], v[42:43], v[12:13]
	v_mul_f32_e32 v42, 0xbfb8aa3b, v24
	v_mul_f32_e32 v43, 0xbfb8aa3b, v25
	v_pk_add_f32 v[28:29], v[28:29], v[44:45]
	v_mul_f32_e32 v44, 0xbfb8aa3b, v46
	v_mul_f32_e32 v45, 0xbfb8aa3b, v47
	v_pk_add_f32 v[10:11], v[48:49], v[10:11]
	v_exp_f32_e32 v52, v42
	v_exp_f32_e32 v53, v43
	v_exp_f32_e32 v54, v44
	v_exp_f32_e32 v55, v45
	v_pk_mul_f32 v[44:45], v[10:11], v[10:11]
	v_mul_f32_e32 v50, 0xbfb8aa3b, v40
	v_pk_mul_f32 v[42:43], v[28:29], v[28:29]
	v_add_f32_e32 v44, v44, v45
	v_mul_f32_e32 v51, 0xbfb8aa3b, v41
	v_exp_f32_e32 v50, v50
	v_add_f32_e32 v42, v42, v44
	v_lshlrev_b32_e32 v22, 16, v26
	v_and_b32_e32 v23, 0xffff0000, v26
	v_pk_add_f32 v[26:27], v[36:37], v[38:39]
	v_pk_mul_f32 v[38:39], v[12:13], v[12:13]
	v_exp_f32_e32 v51, v51
	v_add_f32_e32 v42, v43, v42
	v_add_f32_e32 v43, 1.0, v52
	v_add_f32_e32 v44, 1.0, v53
	v_add_f32_e32 v45, 1.0, v54
	v_add_f32_e32 v52, 1.0, v55
	v_add_f32_e32 v38, v38, v42
	v_pk_mul_f32 v[36:37], v[26:27], v[26:27]
	v_rcp_f32_e32 v42, v43
	v_rcp_f32_e32 v43, v44
	v_rcp_f32_e32 v44, v45
	v_rcp_f32_e32 v45, v52
	v_add_f32_e32 v52, v39, v38
	v_add_f32_e32 v50, 1.0, v50
	v_add_f32_e32 v36, v36, v52
	v_add_f32_e32 v51, 1.0, v51
	v_rcp_f32_e32 v38, v50
	v_add_f32_e32 v50, v37, v36
	v_rcp_f32_e32 v39, v51
	ds_bpermute_b32 v51, v31, v50
	v_mul_f32_e32 v48, 0xbfb8aa3b, v22
	v_mul_f32_e32 v49, 0xbfb8aa3b, v23
	v_pk_mul_f32 v[38:39], v[38:39], v[40:41]
	v_exp_f32_e32 v48, v48
	s_waitcnt lgkmcnt(0)
	v_add_f32_e32 v40, v50, v51
	ds_bpermute_b32 v41, v32, v40
	v_exp_f32_e32 v49, v49
	v_add_f32_e32 v48, 1.0, v48
	v_rcp_f32_e32 v48, v48
	v_pk_mul_f32 v[24:25], v[42:43], v[24:25]
	s_waitcnt lgkmcnt(0)
	v_add_f32_e32 v40, v40, v41
	ds_bpermute_b32 v41, v33, v40
	v_add_f32_e32 v49, 1.0, v49
	v_rcp_f32_e32 v49, v49
	v_pk_mul_f32 v[36:37], v[44:45], v[46:47]
	s_waitcnt lgkmcnt(0)
	v_add_f32_e32 v40, v40, v41
	ds_bpermute_b32 v41, v34, v40
	v_pk_mul_f32 v[22:23], v[48:49], v[22:23]
	s_waitcnt lgkmcnt(0)
	v_add_f32_e32 v40, v40, v41
	v_fmamk_f32 v40, v40, 0x3c000000, v35
	v_mul_f32_e32 v41, 0x4b800000, v40
	v_cmp_gt_f32_e32 vcc, s3, v40
	s_nop 1
	v_cndmask_b32_e32 v40, v40, v41, vcc
	v_rsq_f32_e32 v40, v40
	s_nop 0
	v_mul_f32_e32 v41, 0x45800000, v40
	v_cndmask_b32_e32 v40, v40, v41, vcc
	v_pk_mul_f32 v[10:11], v[10:11], v[40:41] op_sel_hi:[1,0]
	v_pk_mul_f32 v[28:29], v[28:29], v[40:41] op_sel_hi:[1,0]
	v_pk_mul_f32 v[12:13], v[12:13], v[40:41] op_sel_hi:[1,0]
	v_pk_mul_f32 v[26:27], v[26:27], v[40:41] op_sel_hi:[1,0]
	v_pk_mul_f32 v[10:11], v[2:3], v[10:11]
	v_pk_mul_f32 v[28:29], v[4:5], v[28:29]
	v_pk_mul_f32 v[12:13], v[6:7], v[12:13]
	v_pk_mul_f32 v[26:27], v[8:9], v[26:27]
	v_pk_mul_f32 v[10:11], v[22:23], v[10:11]
	v_pk_mul_f32 v[22:23], v[36:37], v[28:29]
	v_pk_mul_f32 v[12:13], v[24:25], v[12:13]
	v_pk_mul_f32 v[24:25], v[38:39], v[26:27]
	v_cvt_pk_bf16_f32 v10, v10, v11
	v_cvt_pk_bf16_f32 v11, v22, v23
	v_cvt_pk_bf16_f32 v12, v12, v13
	v_cvt_pk_bf16_f32 v13, v24, v25
	global_store_dwordx4 v[14:15], v[10:13], off offset:1024
	s_nop 1
	s_waitcnt vmcnt(7)
	v_mov_b32_e32 v10, v152
	v_mov_b32_e32 v11, v153
	v_mov_b32_e32 v12, v154
	v_mov_b32_e32 v13, v155
	v_mov_b32_e32 v22, v156
	v_mov_b32_e32 v23, v157
	v_mov_b32_e32 v24, v158
	v_mov_b32_e32 v25, v159
	v_mov_b32_e32 v26, v160
	v_mov_b32_e32 v27, v161
	v_mov_b32_e32 v28, v162
	v_mov_b32_e32 v29, v163
	s_nop 0
	v_lshlrev_b32_e32 v16, 16, v13
	v_and_b32_e32 v17, 0xffff0000, v13
	v_lshlrev_b32_e32 v18, 16, v25
	v_and_b32_e32 v19, 0xffff0000, v25
	v_lshlrev_b32_e32 v20, 16, v29
	v_and_b32_e32 v21, 0xffff0000, v29
	v_lshlrev_b32_e32 v36, 16, v12
	v_and_b32_e32 v37, 0xffff0000, v12
	v_lshlrev_b32_e32 v12, 16, v24
	v_and_b32_e32 v13, 0xffff0000, v24
	v_lshlrev_b32_e32 v24, 16, v28
	v_and_b32_e32 v25, 0xffff0000, v28
	v_lshlrev_b32_e32 v28, 16, v11
	v_and_b32_e32 v29, 0xffff0000, v11
	v_lshlrev_b32_e32 v38, 16, v23
	v_and_b32_e32 v39, 0xffff0000, v23
	v_lshlrev_b32_e32 v40, 16, v27
	v_and_b32_e32 v41, 0xffff0000, v27
	v_lshlrev_b32_e32 v42, 16, v10
	v_and_b32_e32 v43, 0xffff0000, v10
	v_lshlrev_b32_e32 v10, 16, v22
	v_and_b32_e32 v11, 0xffff0000, v22
	v_pk_add_f32 v[16:17], v[16:17], v[18:19]
	v_pk_add_f32 v[12:13], v[36:37], v[12:13]
	v_mul_f32_e32 v36, 0xbfb8aa3b, v24
	v_mul_f32_e32 v37, 0xbfb8aa3b, v25
	v_pk_add_f32 v[18:19], v[28:29], v[38:39]
	v_mul_f32_e32 v38, 0xbfb8aa3b, v40
	v_mul_f32_e32 v39, 0xbfb8aa3b, v41
	v_pk_add_f32 v[10:11], v[42:43], v[10:11]
	v_exp_f32_e32 v46, v36
	v_exp_f32_e32 v47, v37
	v_exp_f32_e32 v48, v38
	v_exp_f32_e32 v49, v39
	v_pk_mul_f32 v[38:39], v[10:11], v[10:11]
	v_mul_f32_e32 v44, 0xbfb8aa3b, v20
	v_pk_mul_f32 v[36:37], v[18:19], v[18:19]
	v_add_f32_e32 v38, v38, v39
	v_mul_f32_e32 v45, 0xbfb8aa3b, v21
	v_exp_f32_e32 v44, v44
	v_add_f32_e32 v36, v36, v38
	v_pk_mul_f32 v[28:29], v[12:13], v[12:13]
	v_exp_f32_e32 v45, v45
	v_add_f32_e32 v36, v37, v36
	v_add_f32_e32 v37, 1.0, v46
	v_add_f32_e32 v38, 1.0, v47
	v_add_f32_e32 v39, 1.0, v48
	v_add_f32_e32 v46, 1.0, v49
	v_add_f32_e32 v28, v28, v36
	v_lshlrev_b32_e32 v22, 16, v26
	v_and_b32_e32 v23, 0xffff0000, v26
	v_pk_mul_f32 v[26:27], v[16:17], v[16:17]
	v_rcp_f32_e32 v36, v37
	v_rcp_f32_e32 v37, v38
	v_rcp_f32_e32 v38, v39
	v_rcp_f32_e32 v39, v46
	v_add_f32_e32 v46, v29, v28
	v_add_f32_e32 v44, 1.0, v44
	v_add_f32_e32 v26, v26, v46
	v_add_f32_e32 v45, 1.0, v45
	v_rcp_f32_e32 v28, v44
	v_add_f32_e32 v44, v27, v26
	v_rcp_f32_e32 v29, v45
	ds_bpermute_b32 v45, v31, v44
	v_mul_f32_e32 v42, 0xbfb8aa3b, v22
	v_mul_f32_e32 v43, 0xbfb8aa3b, v23
	v_pk_mul_f32 v[20:21], v[28:29], v[20:21]
	v_exp_f32_e32 v42, v42
	s_waitcnt lgkmcnt(0)
	v_add_f32_e32 v28, v44, v45
	ds_bpermute_b32 v29, v32, v28
	v_exp_f32_e32 v43, v43
	v_add_f32_e32 v42, 1.0, v42
	v_rcp_f32_e32 v42, v42
	v_pk_mul_f32 v[24:25], v[36:37], v[24:25]
	s_waitcnt lgkmcnt(0)
	v_add_f32_e32 v28, v28, v29
	ds_bpermute_b32 v29, v33, v28
	v_add_f32_e32 v43, 1.0, v43
	v_rcp_f32_e32 v43, v43
	v_pk_mul_f32 v[26:27], v[38:39], v[40:41]
	s_waitcnt lgkmcnt(0)
	v_add_f32_e32 v28, v28, v29
	ds_bpermute_b32 v29, v34, v28
	v_pk_mul_f32 v[22:23], v[42:43], v[22:23]
	s_waitcnt lgkmcnt(0)
	v_add_f32_e32 v28, v28, v29
	v_fmamk_f32 v28, v28, 0x3c000000, v35
	v_mul_f32_e32 v29, 0x4b800000, v28
	v_cmp_gt_f32_e32 vcc, s3, v28
	s_nop 1
	v_cndmask_b32_e32 v28, v28, v29, vcc
	v_rsq_f32_e32 v28, v28
	s_nop 0
	v_mul_f32_e32 v29, 0x45800000, v28
	v_cndmask_b32_e32 v28, v28, v29, vcc
	v_pk_mul_f32 v[10:11], v[10:11], v[28:29] op_sel_hi:[1,0]
	v_pk_mul_f32 v[18:19], v[18:19], v[28:29] op_sel_hi:[1,0]
	v_pk_mul_f32 v[12:13], v[12:13], v[28:29] op_sel_hi:[1,0]
	v_pk_mul_f32 v[16:17], v[16:17], v[28:29] op_sel_hi:[1,0]
	v_pk_mul_f32 v[10:11], v[2:3], v[10:11]
	v_pk_mul_f32 v[18:19], v[4:5], v[18:19]
	v_pk_mul_f32 v[12:13], v[6:7], v[12:13]
	v_pk_mul_f32 v[16:17], v[8:9], v[16:17]
	v_pk_mul_f32 v[10:11], v[22:23], v[10:11]
	v_pk_mul_f32 v[18:19], v[26:27], v[18:19]
	v_pk_mul_f32 v[12:13], v[24:25], v[12:13]
	v_pk_mul_f32 v[16:17], v[20:21], v[16:17]
	v_cvt_pk_bf16_f32 v10, v10, v11
	v_cvt_pk_bf16_f32 v11, v18, v19
	v_cvt_pk_bf16_f32 v12, v12, v13
	v_cvt_pk_bf16_f32 v13, v16, v17
	global_store_dwordx4 v[14:15], v[10:13], off offset:3072
	s_cbranch_scc0 .LBB0_524
	v_mov_b32_e32 v8, v0
	s_barrier
	s_mov_b32 s3, 0x1fffe0
	v_lshlrev_b32_e32 v2, 4, v8
	v_add_u32_e32 v3, 0x2000, v2
	v_ashrrev_i32_e32 v4, 31, v3
	v_lshrrev_b32_e32 v4, 22, v4
	v_add_u32_e32 v4, v3, v4
	v_ashrrev_i32_e32 v6, 10, v4
	v_mul_i32_i24_e32 v4, 0x400, v6
	v_sub_u32_e32 v3, v3, v4
	v_lshrrev_b32_e32 v4, 4, v3
	v_bitop3_b32 v3, v4, v3, 32 bitop3:0x6c
	v_ashrrev_i32_e32 v4, 31, v3
	v_lshrrev_b32_e32 v4, 26, v4
	v_add_u32_e32 v4, v3, v4
	v_lshlrev_b32_e32 v5, 3, v6
	v_ashrrev_i32_e32 v7, 6, v4
	v_and_b32_e32 v5, -16, v5
	v_add_u32_e32 v5, v7, v5
	v_and_b32_e32 v9, 3, v7
	v_lshrrev_b32_e32 v10, 2, v5
	v_lshlrev_b32_e32 v11, 1, v5
	v_and_b32_e32 v4, 0xc0, v4
	v_and_or_b32 v9, v5, s3, v9
	v_and_b32_e32 v10, 4, v10
	v_and_b32_e32 v11, 24, v11
	v_sub_u32_e32 v3, v3, v4
	v_mov_b32_e32 v4, 1
	v_or3_b32 v10, v9, v10, v11
	v_lshlrev_b32_e32 v9, 5, v6
	v_ashrrev_i16_sdwa v3, v4, sext(v3) dst_sel:DWORD dst_unused:UNUSED_PAD src0_sel:DWORD src1_sel:BYTE_0
	v_and_b32_e32 v11, 32, v9
	v_bfe_i32 v9, v3, 0, 16
	v_add_lshl_u32 v3, v11, v9, 1
	v_lshl_add_u32 v178, v10, 11, v3
	v_lshl_add_u32 v180, v5, 11, v3
	v_bfe_i32 v3, v8, 27, 1
	v_lshrrev_b32_e32 v3, 22, v3
	v_add_u32_e32 v3, v2, v3
	v_and_b32_e32 v3, 0xfffffc00, v3
	v_sub_u32_e32 v2, v2, v3
	v_lshrrev_b32_e32 v3, 4, v2
	v_ashrrev_i32_e32 v5, 31, v8
	v_bitop3_b32 v2, v3, v2, 32 bitop3:0x6c
	v_lshrrev_b32_e32 v5, 26, v5
	v_ashrrev_i32_e32 v3, 31, v2
	v_add_u32_e32 v5, v8, v5
	v_lshrrev_b32_e32 v3, 26, v3
	v_ashrrev_i32_e32 v11, 6, v5
	v_add_u32_e32 v3, v2, v3
	v_lshlrev_b32_e32 v5, 3, v11
	v_ashrrev_i32_e32 v10, 6, v3
	v_and_b32_e32 v5, -16, v5
	v_add_u32_e32 v5, v10, v5
	v_and_b32_e32 v12, 3, v10
	v_lshrrev_b32_e32 v13, 2, v5
	v_lshlrev_b32_e32 v14, 1, v5
	v_and_b32_e32 v3, 0xc0, v3
	v_readfirstlane_b32 s2, v8
	v_and_or_b32 v12, v5, s3, v12
	v_and_b32_e32 v13, 4, v13
	v_and_b32_e32 v14, 24, v14
	v_sub_u32_e32 v2, v2, v3
	s_ashr_i32 s0, s2, 6
	v_or3_b32 v13, v12, v13, v14
	v_lshlrev_b32_e32 v12, 5, v11
	v_ashrrev_i16_sdwa v2, v4, sext(v2) dst_sel:DWORD dst_unused:UNUSED_PAD src0_sel:DWORD src1_sel:BYTE_0
	s_lshl_b32 s12, s0, 10
	v_and_b32_e32 v14, 32, v12
	v_bfe_i32 v12, v2, 0, 16
	v_add_lshl_u32 v2, v14, v12, 1
	s_add_i32 s3, s12, 0
	v_lshl_add_u32 v182, v13, 11, v2
	s_add_i32 m0, s3, 0x10000
	s_ashr_i32 s1, s2, 8
	global_load_lds_dwordx4 v182, s[88:89]
	s_add_i32 m0, s3, 0x12000
	s_add_u32 s6, s80, s8
	v_lshl_add_u32 v190, v5, 11, v2
	global_load_lds_dwordx4 v178, s[88:89]
	s_addc_u32 s7, s81, s9
	s_mov_b32 m0, s3
	s_add_i32 s20, s3, 0x2000
	global_load_lds_dwordx4 v190, s[6:7]
	s_mov_b32 m0, s20
	s_add_u32 s14, s80, 0x36940000
	global_load_lds_dwordx4 v180, s[6:7]
	s_addc_u32 s15, s81, 0
	s_add_i32 m0, s3, 0x14000
	v_mov_b32_e32 v183, 0
	global_load_lds_dwordx4 v182, s[14:15]
	s_add_i32 m0, s3, 0x16000
	v_mov_b32_e32 v191, v183
	global_load_lds_dwordx4 v178, s[14:15]
	s_add_u32 s14, s6, 0x40000
	s_addc_u32 s15, s7, 0
	s_add_i32 s21, s3, 0x4000
	s_mov_b32 m0, s21
	s_add_i32 s22, s3, 0x6000
	global_load_lds_dwordx4 v190, s[14:15]
	s_mov_b32 m0, s22
	v_mov_b32_e32 v181, v183
	global_load_lds_dwordx4 v180, s[14:15]
	s_mov_b32 s23, 0
	v_mov_b32_e32 v179, v183
	v_lshl_add_u64 v[4:5], s[6:7], 0, v[190:191]
	s_cmp_lg_u32 s1, 1
	v_lshl_add_u64 v[2:3], s[6:7], 0, v[180:181]
	s_cbranch_scc1 .LBB0_527
	s_barrier
